# attention main loop: unconditional LDS-DMA pieces with fixed vmcnt(3), no m0 save/restore, far-path shortcut (scalar control trimmed)
# speedup vs baseline: 1.0076x; 1.0076x over previous
; #define SBAR() __builtin_amdgcn_sched_barrier(0)
; #define KRD(d0) do { if constexpr (VAR & 4) break; const char* a_ = Kc + (((2 * (d0) + hi) ^ sw) << 4); ka[d0] = *reinterpret_cast<const bf16x8*>(a_); kb[d0] = *reinterpret_cast<const bf16x8*>(a_ + 32 * 128); } while (0)
; #define PKA(Y, b) do { if constexpr (!(VAR & 8)) { a0 = cvtpk(Y[b], Y[(b) + 1]); a1 = cvtpk(Y[(b) + 2], Y[(b) + 3]); } } while (0)
; template <int VAR> ...
;     ...
;     ka[0] = kp[0]; kb[0] = kp[1]; ka[1] = kp[2]; kb[1] = kp[3]; if (dk) glds16(gk, lk); SBAR();
;     { const f32x16 z = f32x16{};
;       QKM(x0, ka[0], qr[0], z);  SUM4(y0, 0); PKA(y0, 0);       SBAR();
;       QKM(x1, kb[0], qr[0], z);  SUM4(y0, 4); PKB(y0, 4, pa0);  KRD(2); if (dv) glds16(gv, lv); SBAR(); }
;     QKM(x0, ka[1], qr[1], x0); SUM4(y0, 8); PKA(y0, 8);       SBAR();
;     QKM(x1, kb[1], qr[1], x1); SUM4(y0, 12); PKB(y0, 12, pa1); KRD(3); if (dv) glds16(gv + 8192, lv + 8192); SBAR();
;     QKM(x0, ka[2], qr[2], x0); SUM4(y1, 0); PKA(y1, 0);       SBAR();
;     QKM(x1, kb[2], qr[2], x1); SUM4(y1, 4); PKB(y1, 4, pa2);  SBAR();
;     QKM(x0, ka[3], qr[3], x0); SUM4(y1, 8); PKA(y1, 8);       SBAR();
;     QKM(x1, kb[3], qr[3], x1); SUM4(y1, 12); PKB(y1, 12, pa3); VRD(0); VRD(1); SBAR();
;     VRD(2); VRD(3); SBAR();
;     if (near) {
;         float tA[4], uA[4], tB[4], uB[4];
;     ...
;         TLD(tA, uA, 0); SBAR(); TLD(tB, uB, 1); SBAR();
;         asm volatile("s_nop 15\n\ts_nop 7" : "+v"(x0), "+v"(x1));
;         TAD(tA, uA, 0); SBAR(); TLD(tA, uA, 2); SBAR(); TAD(tB, uB, 1); SBAR(); TLD(tB, uB, 3); SBAR(); TAD(tA, uA, 2); SBAR(); TAD(tB, uB, 3);
;     ...
;     } else if (__builtin_expect(shift != 0.f, 0)) {
;         asm volatile("s_nop 15\n\ts_nop 7" : "+v"(x0), "+v"(x1));
; #pragma unroll
;         for (int r = 0; r < 16; ++r) { asm volatile("v_sub_f32 %0, %0, %1" : "+v"(x0[r]) : "v"(shift)); asm volatile("v_sub_f32 %0, %0, %1" : "+v"(x1[r]) : "v"(shift)); }
;     }
;     SBAR();
;     ...
;     GAPB(0, pa0); GAPB(1, pa1); GAPB(2, pa2); GAPB(3, pa3); GAPB(4, pa0); GAPB(5, pa1); GAPB(6, pa2); GAPB(7, pa3);
;     GAPB(8, pa0); GAPB(9, pa1); GAPB(10, pa2); GAPB(11, pa3);
;     if (wv == 3) asm volatile("s_waitcnt vmcnt(3)" ::: "memory"); else if (wv == 2) asm volatile("s_waitcnt vmcnt(2)" ::: "memory"); else asm volatile("s_waitcnt vmcnt(0)" ::: "memory");
;     asm volatile("s_waitcnt lgkmcnt(0)\n\ts_barrier" ::: "memory");
.LBB0_356:
	s_lshl_b32 s0, s67, 13
	s_lshl_b32 s1, s86, 14
	s_add_i32 s90, s20, 1
	s_add_i32 s0, s0, s88
	s_add_i32 s66, s1, s87
	v_lshl_add_u64 v[4:5], v[206:207], 0, s[44:45]
	s_mov_b32 m0, s0
	s_lshl_b32 s92, s91, 13
	global_load_lds_dwordx4 v[4:5], off
	v_add_u32_e32 v12, s92, v215
	s_waitcnt lgkmcnt(3)
	v_mfma_f32_32x32x16_bf16 v[130:145], v[174:177], v[146:149], 0
	v_add_f32_e32 v4, v82, v83
	v_add_f32_e32 v5, v84, v85
	v_add_f32_e32 v4, v4, v5
	v_add_f32_e32 v6, 0, v4
	v_cvt_pk_bf16_f32 v4, v82, v83
	v_cvt_pk_bf16_f32 v5, v84, v85
	v_add_f32_e32 v7, v86, v87
	v_add_f32_e32 v8, v88, v89
	s_waitcnt lgkmcnt(2)
	v_mfma_f32_32x32x16_bf16 v[114:129], v[170:173], v[146:149], 0
	v_add_f32_e32 v7, v7, v8
	v_add_f32_e32 v8, v7, v6
	v_cvt_pk_bf16_f32 v6, v86, v87
	v_cvt_pk_bf16_f32 v7, v88, v89
	v_add_u32_e32 v9, v12, v218
	s_mov_b32 m0, s66
	ds_read_b128 v[14:17], v9 offset:49152
	ds_read_b128 v[86:89], v9 offset:53248
	global_load_lds_dwordx4 v[208:209], off
	s_waitcnt lgkmcnt(3)
	v_mfma_f32_32x32x16_bf16 v[130:145], v[166:169], v[150:153], v[130:145]
	v_add_f32_e32 v9, v90, v91
	v_add_f32_e32 v10, v92, v93
	v_add_f32_e32 v9, v9, v10
	v_add_f32_e32 v10, v9, v8
	v_cvt_pk_bf16_f32 v8, v90, v91
	v_cvt_pk_bf16_f32 v9, v92, v93
	v_add_f32_e32 v11, v94, v95
	v_add_f32_e32 v13, v96, v97
	s_waitcnt lgkmcnt(2)
	v_mfma_f32_32x32x16_bf16 v[114:129], v[162:165], v[150:153], v[114:129]
	v_add_f32_e32 v11, v11, v13
	v_add_f32_e32 v13, v11, v10
	v_cvt_pk_bf16_f32 v10, v94, v95
	v_cvt_pk_bf16_f32 v11, v96, v97
	v_add_u32_e32 v12, v12, v219
	ds_read_b128 v[90:93], v12 offset:49152
	ds_read_b128 v[82:85], v12 offset:53248
	s_add_i32 m0, s66, 0x2000
	v_lshl_add_u64 v[94:95], v[208:209], 0, s[22:23]
	global_load_lds_dwordx4 v[94:95], off
	s_lshl_b32 s2, s67, 14
	s_sub_i32 s66, s89, 64
	s_cmp_le_i32 s66, s85
	s_waitcnt lgkmcnt(3)
	v_mfma_f32_32x32x16_bf16 v[130:145], v[14:17], v[154:157], v[130:145]
	v_add_f32_e32 v12, v98, v99
	v_add_f32_e32 v94, v100, v101
	v_add_f32_e32 v12, v12, v94
	v_add_f32_e32 v94, v12, v13
	v_cvt_pk_bf16_f32 v12, v98, v99
	v_cvt_pk_bf16_f32 v13, v100, v101
	s_waitcnt lgkmcnt(2)
	v_mfma_f32_32x32x16_bf16 v[114:129], v[86:89], v[154:157], v[114:129]
	v_add_f32_e32 v14, v102, v103
	v_add_f32_e32 v15, v104, v105
	v_add_f32_e32 v14, v14, v15
	v_add_f32_e32 v16, v14, v94
	v_cvt_pk_bf16_f32 v14, v102, v103
	v_cvt_pk_bf16_f32 v15, v104, v105
	s_waitcnt lgkmcnt(1)
	v_mfma_f32_32x32x16_bf16 v[130:145], v[90:93], v[158:161], v[130:145]
	v_add_f32_e32 v17, v106, v107
	v_add_f32_e32 v86, v108, v109
	v_add_f32_e32 v17, v17, v86
	v_add_f32_e32 v16, v17, v16
	v_cvt_pk_bf16_f32 v178, v106, v107
	v_cvt_pk_bf16_f32 v179, v108, v109
	v_add_f32_e32 v17, v110, v111
	v_add_f32_e32 v86, v112, v113
	v_add_f32_e32 v17, v17, v86
	v_add_f32_e32 v229, v17, v16
	v_cvt_pk_bf16_f32 v180, v110, v111
	v_cvt_pk_bf16_f32 v181, v112, v113
	v_add_u32_e32 v16, s2, v214
	s_waitcnt lgkmcnt(0)
	v_mfma_f32_32x32x16_bf16 v[114:129], v[82:85], v[158:161], v[114:129]
	ds_read_b64_tr_b16 v[174:175], v16
	ds_read_b64_tr_b16 v[176:177], v16 offset:256
	ds_read_b64_tr_b16 v[170:171], v16 offset:4096
	ds_read_b64_tr_b16 v[172:173], v16 offset:4352
	ds_read_b64_tr_b16 v[166:167], v16 offset:8192
	ds_read_b64_tr_b16 v[168:169], v16 offset:8448
	ds_read_b64_tr_b16 v[162:163], v16 offset:12288
	ds_read_b64_tr_b16 v[164:165], v16 offset:12544
	s_cbranch_scc0 .LBB0_396
	v_mov_b64_e32 v[82:83], v[130:131]
	s_and_b64 vcc, exec, s[4:5]
	v_mov_b64_e32 v[84:85], v[132:133]
	v_mov_b64_e32 v[86:87], v[134:135]
	v_mov_b64_e32 v[88:89], v[136:137]
	v_mov_b64_e32 v[90:91], v[138:139]
	v_mov_b64_e32 v[92:93], v[140:141]
	v_mov_b64_e32 v[94:95], v[142:143]
	v_mov_b64_e32 v[96:97], v[144:145]
	s_cbranch_vccnz .Lp2t_shift1
.LBB0_367:
	s_waitcnt lgkmcnt(6)
	v_mfma_f32_32x32x16_bf16 v[66:81], v[4:7], v[174:177], v[66:81]
	v_exp_f32_e32 v82, v82
	v_exp_f32_e32 v114, v114
	ds_read_b64_tr_b16 v[98:99], v16 offset:512
	ds_read_b64_tr_b16 v[100:101], v16 offset:768
	s_waitcnt lgkmcnt(6)
	v_mfma_f32_32x32x16_bf16 v[66:81], v[8:11], v[170:173], v[66:81]
	v_exp_f32_e32 v83, v83
	v_exp_f32_e32 v115, v115
	ds_read_b64_tr_b16 v[102:103], v16 offset:4608
	ds_read_b64_tr_b16 v[104:105], v16 offset:4864
	s_waitcnt lgkmcnt(6)
	v_mfma_f32_32x32x16_bf16 v[66:81], v[12:15], v[166:169], v[66:81]
	v_exp_f32_e32 v84, v84
	v_exp_f32_e32 v116, v116
	ds_read_b64_tr_b16 v[106:107], v16 offset:8704
	ds_read_b64_tr_b16 v[108:109], v16 offset:8960
	s_waitcnt lgkmcnt(6)
	v_mfma_f32_32x32x16_bf16 v[66:81], v[178:181], v[162:165], v[66:81]
	v_exp_f32_e32 v85, v85
	v_exp_f32_e32 v117, v117
	ds_read_b64_tr_b16 v[110:111], v16 offset:12800
	ds_read_b64_tr_b16 v[112:113], v16 offset:13056
	s_waitcnt lgkmcnt(6)
	v_mfma_f32_32x32x16_bf16 v[50:65], v[4:7], v[98:101], v[50:65]
	v_exp_f32_e32 v86, v86
	v_exp_f32_e32 v118, v118
	ds_read_b64_tr_b16 v[130:131], v16 offset:1024
	ds_read_b64_tr_b16 v[132:133], v16 offset:1280
	s_waitcnt lgkmcnt(6)
	v_mfma_f32_32x32x16_bf16 v[50:65], v[8:11], v[102:105], v[50:65]
	v_exp_f32_e32 v87, v87
	v_exp_f32_e32 v119, v119
	ds_read_b64_tr_b16 v[134:135], v16 offset:5120
	ds_read_b64_tr_b16 v[136:137], v16 offset:5376
	s_waitcnt lgkmcnt(6)
	v_mfma_f32_32x32x16_bf16 v[50:65], v[12:15], v[106:109], v[50:65]
	v_exp_f32_e32 v88, v88
	v_exp_f32_e32 v120, v120
	ds_read_b64_tr_b16 v[138:139], v16 offset:9216
	ds_read_b64_tr_b16 v[140:141], v16 offset:9472
	s_waitcnt lgkmcnt(6)
	v_mfma_f32_32x32x16_bf16 v[50:65], v[178:181], v[110:113], v[50:65]
	v_exp_f32_e32 v89, v89
	v_exp_f32_e32 v121, v121
	ds_read_b64_tr_b16 v[142:143], v16 offset:13312
	ds_read_b64_tr_b16 v[144:145], v16 offset:13568
	s_waitcnt lgkmcnt(6)
	v_mfma_f32_32x32x16_bf16 v[34:49], v[4:7], v[130:133], v[34:49]
	v_exp_f32_e32 v90, v90
	v_exp_f32_e32 v122, v122
	ds_read_b64_tr_b16 v[98:99], v16 offset:1536
	ds_read_b64_tr_b16 v[100:101], v16 offset:1792
	s_waitcnt lgkmcnt(6)
	v_mfma_f32_32x32x16_bf16 v[34:49], v[8:11], v[134:137], v[34:49]
	v_exp_f32_e32 v91, v91
	v_exp_f32_e32 v123, v123
	ds_read_b64_tr_b16 v[102:103], v16 offset:5632
	ds_read_b64_tr_b16 v[104:105], v16 offset:5888
	s_waitcnt lgkmcnt(6)
	v_mfma_f32_32x32x16_bf16 v[34:49], v[12:15], v[138:141], v[34:49]
	v_exp_f32_e32 v92, v92
	v_exp_f32_e32 v124, v124
	ds_read_b64_tr_b16 v[106:107], v16 offset:9728
	ds_read_b64_tr_b16 v[108:109], v16 offset:9984
	s_waitcnt lgkmcnt(6)
	v_mfma_f32_32x32x16_bf16 v[34:49], v[178:181], v[142:145], v[34:49]
	v_exp_f32_e32 v93, v93
	v_exp_f32_e32 v125, v125
	ds_read_b64_tr_b16 v[110:111], v16 offset:13824
	ds_read_b64_tr_b16 v[112:113], v16 offset:14080
	s_waitcnt vmcnt(3)
	v_lshl_add_u32 v182, s86, 13, v215
	s_waitcnt lgkmcnt(0)
	s_barrier
; #define SBAR() __builtin_amdgcn_sched_barrier(0)
; #define KRD(d0) do { if constexpr (VAR & 4) break; const char* a_ = Kc + (((2 * (d0) + hi) ^ sw) << 4); ka[d0] = *reinterpret_cast<const bf16x8*>(a_); kb[d0] = *reinterpret_cast<const bf16x8*>(a_ + 32 * 128); } while (0)
; #define VRD(i) do { if constexpr (VAR & 2) break; lo[(i) & 3] = vtr(vb + v_rd_off((i) >> 2, (i) & 3, 0)); hv[(i) & 3] = vtr(vb + v_rd_off((i) >> 2, (i) & 3, 1)); } while (0)
; #define SUM4(Y, b) do { if constexpr (!(VAR & 8)) { ps += (Y[b] + Y[(b) + 1]) + (Y[(b) + 2] + Y[(b) + 3]); asm volatile("" : "+v"(ps)); } } while (0)
; #define PKA(Y, b) do { if constexpr (!(VAR & 8)) { a0 = cvtpk(Y[b], Y[(b) + 1]); a1 = cvtpk(Y[(b) + 2], Y[(b) + 3]); } } while (0)
; #define PKB(Y, b, OUT) do { if constexpr (VAR & 8) { OUT = ka[0]; asm volatile("" : "+v"(OUT)); } else { b0 = cvtpk(Y[b], Y[(b) + 1]); b1 = cvtpk(Y[(b) + 2], Y[(b) + 3]); u32x4 w_ = {a0, a1, b0, b1}; OUT = *reinterpret_cast<bf16x8*>(&w_); asm volatile("" : "+v"(OUT)); } } while (0)
; template <int VAR> ...
;     ...
;     ka[0] = kp[0]; kb[0] = kp[1]; ka[1] = kp[2]; kb[1] = kp[3]; if (dk) glds16(gk, lk); SBAR();
;     { const f32x16 z = f32x16{};
;       QKM(x0, ka[0], qr[0], z);  SUM4(y0, 0); PKA(y0, 0);       SBAR();
;       QKM(x1, kb[0], qr[0], z);  SUM4(y0, 4); PKB(y0, 4, pa0);  KRD(2); if (dv) glds16(gv, lv); SBAR(); }
;     QKM(x0, ka[1], qr[1], x0); SUM4(y0, 8); PKA(y0, 8);       SBAR();
;     QKM(x1, kb[1], qr[1], x1); SUM4(y0, 12); PKB(y0, 12, pa1); KRD(3); if (dv) glds16(gv + 8192, lv + 8192); SBAR();
;     QKM(x0, ka[2], qr[2], x0); SUM4(y1, 0); PKA(y1, 0);       SBAR();
;     QKM(x1, kb[2], qr[2], x1); SUM4(y1, 4); PKB(y1, 4, pa2);  SBAR();
;     QKM(x0, ka[3], qr[3], x0); SUM4(y1, 8); PKA(y1, 8);       SBAR();
;     QKM(x1, kb[3], qr[3], x1); SUM4(y1, 12); PKB(y1, 12, pa3); VRD(0); VRD(1); SBAR();
;     ...
;     GAPB(0, pa0); GAPB(1, pa1); GAPB(2, pa2); GAPB(3, pa3); GAPB(4, pa0); GAPB(5, pa1); GAPB(6, pa2); GAPB(7, pa3);
;     GAPB(8, pa0); GAPB(9, pa1); GAPB(10, pa2); GAPB(11, pa3);
;     if (wv == 3) asm volatile("s_waitcnt vmcnt(3)" ::: "memory"); else if (wv == 2) asm volatile("s_waitcnt vmcnt(2)" ::: "memory"); else asm volatile("s_waitcnt vmcnt(0)" ::: "memory");
;     asm volatile("s_waitcnt lgkmcnt(0)\n\ts_barrier" ::: "memory");
	v_add_u32_e32 v16, v182, v216
	v_add_u32_e32 v17, v182, v217
	ds_read_b128 v[174:177], v16 offset:49152
	ds_read_b128 v[170:173], v16 offset:53248
	ds_read_b128 v[166:169], v17 offset:49152
	ds_read_b128 v[162:165], v17 offset:53248
	s_waitcnt lgkmcnt(10)
	v_mfma_f32_32x32x16_bf16 v[18:33], v[4:7], v[98:101], v[18:33]
	v_exp_f32_e32 v94, v94
	v_exp_f32_e32 v126, v126
	s_waitcnt lgkmcnt(8)
	v_mfma_f32_32x32x16_bf16 v[18:33], v[8:11], v[102:105], v[18:33]
	v_exp_f32_e32 v95, v95
	v_exp_f32_e32 v127, v127
	s_waitcnt lgkmcnt(6)
	v_mfma_f32_32x32x16_bf16 v[18:33], v[12:15], v[106:109], v[18:33]
	v_exp_f32_e32 v96, v96
	v_exp_f32_e32 v128, v128
	s_waitcnt lgkmcnt(4)
	v_mfma_f32_32x32x16_bf16 v[18:33], v[178:181], v[110:113], v[18:33]
	v_exp_f32_e32 v97, v97
	v_exp_f32_e32 v129, v129
	s_add_i32 s0, s86, 1
	s_cmp_lg_u32 s86, 2
	s_cselect_b32 s68, s0, 0
	s_lshl_b32 s1, s68, 14
	s_add_i32 s20, s20, 2
	s_add_i32 m0, s92, s88
	s_add_i32 s69, s1, s87
	global_load_lds_dwordx4 v[206:207], off
	v_lshl_add_u64 v[12:13], v[208:209], 0, s[26:27]
	s_waitcnt lgkmcnt(3)
	v_mfma_f32_32x32x16_bf16 v[130:145], v[174:177], v[146:149], 0
	v_add_f32_e32 v4, v82, v83
	v_add_f32_e32 v5, v84, v85
	v_add_f32_e32 v4, v4, v5
	v_add_f32_e32 v6, 0, v4
	v_cvt_pk_bf16_f32 v4, v82, v83
	v_cvt_pk_bf16_f32 v5, v84, v85
	v_add_f32_e32 v7, v86, v87
	v_add_f32_e32 v8, v88, v89
	s_waitcnt lgkmcnt(2)
	v_mfma_f32_32x32x16_bf16 v[98:113], v[170:173], v[146:149], 0
	v_add_f32_e32 v7, v7, v8
	v_add_f32_e32 v8, v7, v6
	v_cvt_pk_bf16_f32 v6, v86, v87
	v_cvt_pk_bf16_f32 v7, v88, v89
	v_add_u32_e32 v9, v182, v218
	s_mov_b32 m0, s69
	ds_read_b128 v[14:17], v9 offset:49152
	ds_read_b128 v[82:85], v9 offset:53248
	global_load_lds_dwordx4 v[12:13], off
	s_waitcnt lgkmcnt(3)
	v_mfma_f32_32x32x16_bf16 v[130:145], v[166:169], v[150:153], v[130:145]
	v_add_f32_e32 v9, v90, v91
	v_add_f32_e32 v10, v92, v93
	v_add_f32_e32 v9, v9, v10
	v_add_f32_e32 v10, v9, v8
	v_cvt_pk_bf16_f32 v8, v90, v91
	v_cvt_pk_bf16_f32 v9, v92, v93
	v_add_f32_e32 v11, v94, v95
	v_add_f32_e32 v86, v96, v97
	s_waitcnt lgkmcnt(2)
	v_mfma_f32_32x32x16_bf16 v[98:113], v[162:165], v[150:153], v[98:113]
	v_add_f32_e32 v11, v11, v86
	v_add_f32_e32 v178, v11, v10
	v_cvt_pk_bf16_f32 v10, v94, v95
	v_cvt_pk_bf16_f32 v11, v96, v97
	v_add_u32_e32 v86, v182, v219
	ds_read_b128 v[90:93], v86 offset:49152
	ds_read_b128 v[86:89], v86 offset:53248
	s_add_i32 m0, s69, 0x2000
	v_lshl_add_u64 v[12:13], v[12:13], 0, s[22:23]
	global_load_lds_dwordx4 v[12:13], off
	s_lshl_b32 s0, s91, 14
	s_cmp_le_i32 s89, s85
	s_waitcnt lgkmcnt(3)
	v_mfma_f32_32x32x16_bf16 v[130:145], v[14:17], v[154:157], v[130:145]
	v_add_f32_e32 v12, v114, v115
	v_add_f32_e32 v13, v116, v117
	v_add_f32_e32 v12, v12, v13
	v_add_f32_e32 v94, v12, v178
	v_cvt_pk_bf16_f32 v12, v114, v115
	v_cvt_pk_bf16_f32 v13, v116, v117
	s_waitcnt lgkmcnt(2)
	v_mfma_f32_32x32x16_bf16 v[98:113], v[82:85], v[154:157], v[98:113]
	v_add_f32_e32 v14, v118, v119
	v_add_f32_e32 v15, v120, v121
	v_add_f32_e32 v14, v14, v15
	v_add_f32_e32 v16, v14, v94
	v_cvt_pk_bf16_f32 v14, v118, v119
	v_cvt_pk_bf16_f32 v15, v120, v121
	s_waitcnt lgkmcnt(1)
	v_mfma_f32_32x32x16_bf16 v[130:145], v[90:93], v[158:161], v[130:145]
	v_add_f32_e32 v17, v122, v123
	v_add_f32_e32 v82, v124, v125
	v_add_f32_e32 v17, v17, v82
	v_add_f32_e32 v16, v17, v16
	v_cvt_pk_bf16_f32 v178, v122, v123
	v_cvt_pk_bf16_f32 v179, v124, v125
	v_add_f32_e32 v17, v126, v127
	v_add_f32_e32 v82, v128, v129
	v_add_f32_e32 v17, v17, v82
	v_add_f32_e32 v16, v17, v16
	v_cvt_pk_bf16_f32 v180, v126, v127
	v_cvt_pk_bf16_f32 v181, v128, v129
	v_add_u32_e32 v17, s0, v214
	s_waitcnt lgkmcnt(0)
	v_mfma_f32_32x32x16_bf16 v[98:113], v[86:89], v[158:161], v[98:113]
	ds_read_b64_tr_b16 v[194:195], v17
	ds_read_b64_tr_b16 v[196:197], v17 offset:256
	ds_read_b64_tr_b16 v[190:191], v17 offset:4096
	ds_read_b64_tr_b16 v[192:193], v17 offset:4352
	ds_read_b64_tr_b16 v[186:187], v17 offset:8192
	ds_read_b64_tr_b16 v[188:189], v17 offset:8448
	ds_read_b64_tr_b16 v[182:183], v17 offset:12288
	ds_read_b64_tr_b16 v[184:185], v17 offset:12544
	s_cbranch_scc0 .LBB0_398
	v_mov_b64_e32 v[82:83], v[130:131]
	s_and_b64 vcc, exec, s[4:5]
	v_mov_b64_e32 v[84:85], v[132:133]
	v_mov_b64_e32 v[86:87], v[134:135]
	v_mov_b64_e32 v[88:89], v[136:137]
	v_mov_b64_e32 v[90:91], v[138:139]
	v_mov_b64_e32 v[92:93], v[140:141]
	v_mov_b64_e32 v[94:95], v[142:143]
	v_mov_b64_e32 v[96:97], v[144:145]
	s_cbranch_vccnz .Lp2t_shift2
; template <int VAR> ...
;     ...
;     GAPB(0, pa0); GAPB(1, pa1); GAPB(2, pa2); GAPB(3, pa3); GAPB(4, pa0); GAPB(5, pa1); GAPB(6, pa2); GAPB(7, pa3);
;     GAPB(8, pa0); GAPB(9, pa1); GAPB(10, pa2); GAPB(11, pa3);
;     if (wv == 3) asm volatile("s_waitcnt vmcnt(3)" ::: "memory"); else if (wv == 2) asm volatile("s_waitcnt vmcnt(2)" ::: "memory"); else asm volatile("s_waitcnt vmcnt(0)" ::: "memory");
;     asm volatile("s_waitcnt lgkmcnt(0)\n\ts_barrier" ::: "memory");
.LBB0_385:
	s_waitcnt lgkmcnt(6)
	v_mfma_f32_32x32x16_bf16 v[66:81], v[4:7], v[194:197], v[66:81]
	v_exp_f32_e32 v82, v82
	v_exp_f32_e32 v98, v98
	ds_read_b64_tr_b16 v[114:115], v17 offset:512
	ds_read_b64_tr_b16 v[116:117], v17 offset:768
	s_waitcnt lgkmcnt(6)
	v_mfma_f32_32x32x16_bf16 v[66:81], v[8:11], v[190:193], v[66:81]
	v_exp_f32_e32 v83, v83
	v_exp_f32_e32 v99, v99
	ds_read_b64_tr_b16 v[118:119], v17 offset:4608
	ds_read_b64_tr_b16 v[120:121], v17 offset:4864
	s_waitcnt lgkmcnt(6)
	v_mfma_f32_32x32x16_bf16 v[66:81], v[12:15], v[186:189], v[66:81]
	v_exp_f32_e32 v84, v84
	v_exp_f32_e32 v100, v100
	ds_read_b64_tr_b16 v[122:123], v17 offset:8704
	ds_read_b64_tr_b16 v[124:125], v17 offset:8960
	s_waitcnt lgkmcnt(6)
	v_mfma_f32_32x32x16_bf16 v[66:81], v[178:181], v[182:185], v[66:81]
	v_exp_f32_e32 v85, v85
	v_exp_f32_e32 v101, v101
	ds_read_b64_tr_b16 v[126:127], v17 offset:12800
	ds_read_b64_tr_b16 v[128:129], v17 offset:13056
	s_waitcnt lgkmcnt(6)
	v_mfma_f32_32x32x16_bf16 v[50:65], v[4:7], v[114:117], v[50:65]
	v_exp_f32_e32 v86, v86
	v_exp_f32_e32 v102, v102
	ds_read_b64_tr_b16 v[130:131], v17 offset:1024
	ds_read_b64_tr_b16 v[132:133], v17 offset:1280
	s_waitcnt lgkmcnt(6)
	v_mfma_f32_32x32x16_bf16 v[50:65], v[8:11], v[118:121], v[50:65]
	v_exp_f32_e32 v87, v87
	v_exp_f32_e32 v103, v103
	ds_read_b64_tr_b16 v[134:135], v17 offset:5120
	ds_read_b64_tr_b16 v[136:137], v17 offset:5376
	s_waitcnt lgkmcnt(6)
	v_mfma_f32_32x32x16_bf16 v[50:65], v[12:15], v[122:125], v[50:65]
	v_exp_f32_e32 v88, v88
	v_exp_f32_e32 v104, v104
	ds_read_b64_tr_b16 v[138:139], v17 offset:9216
	ds_read_b64_tr_b16 v[140:141], v17 offset:9472
	s_waitcnt lgkmcnt(6)
	v_mfma_f32_32x32x16_bf16 v[50:65], v[178:181], v[126:129], v[50:65]
	v_exp_f32_e32 v89, v89
	v_exp_f32_e32 v105, v105
	ds_read_b64_tr_b16 v[142:143], v17 offset:13312
	ds_read_b64_tr_b16 v[144:145], v17 offset:13568
	s_waitcnt lgkmcnt(6)
	v_mfma_f32_32x32x16_bf16 v[34:49], v[4:7], v[130:133], v[34:49]
	v_exp_f32_e32 v90, v90
	v_exp_f32_e32 v106, v106
	ds_read_b64_tr_b16 v[114:115], v17 offset:1536
	ds_read_b64_tr_b16 v[116:117], v17 offset:1792
	s_waitcnt lgkmcnt(6)
	v_mfma_f32_32x32x16_bf16 v[34:49], v[8:11], v[134:137], v[34:49]
	v_exp_f32_e32 v91, v91
	v_exp_f32_e32 v107, v107
	ds_read_b64_tr_b16 v[118:119], v17 offset:5632
	ds_read_b64_tr_b16 v[120:121], v17 offset:5888
	s_waitcnt lgkmcnt(6)
	v_mfma_f32_32x32x16_bf16 v[34:49], v[12:15], v[138:141], v[34:49]
	v_exp_f32_e32 v92, v92
	v_exp_f32_e32 v108, v108
	ds_read_b64_tr_b16 v[122:123], v17 offset:9728
	ds_read_b64_tr_b16 v[124:125], v17 offset:9984
	s_waitcnt lgkmcnt(6)
	v_mfma_f32_32x32x16_bf16 v[34:49], v[178:181], v[142:145], v[34:49]
	v_exp_f32_e32 v93, v93
	v_exp_f32_e32 v109, v109
	ds_read_b64_tr_b16 v[126:127], v17 offset:13824
	ds_read_b64_tr_b16 v[128:129], v17 offset:14080
	s_waitcnt vmcnt(3)
	s_waitcnt lgkmcnt(0)
	s_barrier
	s_cmp_gt_i32 s90, s60
	s_cbranch_scc1 .LBB0_394
	v_lshl_add_u32 v17, s68, 13, v215
	v_add_u32_e32 v130, v17, v216
	v_add_u32_e32 v17, v17, v217
	ds_read_b128 v[174:177], v130 offset:49152
	ds_read_b128 v[170:173], v130 offset:53248
	ds_read_b128 v[166:169], v17 offset:49152
	ds_read_b128 v[162:165], v17 offset:53248

; template <int VAR> ...
;     ...
;     } else if (__builtin_expect(shift != 0.f, 0)) {
;         asm volatile("s_nop 15\n\ts_nop 7" : "+v"(x0), "+v"(x1));
; #pragma unroll
;         for (int r = 0; r < 16; ++r) { asm volatile("v_sub_f32 %0, %0, %1" : "+v"(x0[r]) : "v"(shift)); asm volatile("v_sub_f32 %0, %0, %1" : "+v"(x1[r]) : "v"(shift)); }
;     }
.Lp2t_shift1:
	s_mov_b64 s[66:67], 0
	s_mov_b64 s[68:69], 0
	s_branch .LBB0_400

; #define SBAR() __builtin_amdgcn_sched_barrier(0)
; template <int VAR> ...
;     ...
;     } else if (__builtin_expect(shift != 0.f, 0)) {
;         asm volatile("s_nop 15\n\ts_nop 7" : "+v"(x0), "+v"(x1));
; #pragma unroll
;         for (int r = 0; r < 16; ++r) { asm volatile("v_sub_f32 %0, %0, %1" : "+v"(x0[r]) : "v"(shift)); asm volatile("v_sub_f32 %0, %0, %1" : "+v"(x1[r]) : "v"(shift)); }
;     }
;     SBAR();
.LBB0_366:
	v_mov_b64_e32 v[128:129], v[112:113]
	v_mov_b64_e32 v[126:127], v[110:111]
	v_mov_b64_e32 v[124:125], v[108:109]
	v_mov_b64_e32 v[122:123], v[106:107]
	v_mov_b64_e32 v[120:121], v[104:105]
	v_mov_b64_e32 v[118:119], v[102:103]
	v_mov_b64_e32 v[116:117], v[100:101]
	v_mov_b64_e32 v[114:115], v[98:99]
	s_branch .LBB0_367
.Lp2t_shift2:
	s_mov_b64 s[0:1], 0
	s_mov_b64 s[64:65], 0
	s_branch .LBB0_401

; #define SBAR() __builtin_amdgcn_sched_barrier(0)
; template <int VAR> ...
;     ...
;     } else if (__builtin_expect(shift != 0.f, 0)) {
;         asm volatile("s_nop 15\n\ts_nop 7" : "+v"(x0), "+v"(x1));
; #pragma unroll
;         for (int r = 0; r < 16; ++r) { asm volatile("v_sub_f32 %0, %0, %1" : "+v"(x0[r]) : "v"(shift)); asm volatile("v_sub_f32 %0, %0, %1" : "+v"(x1[r]) : "v"(shift)); }
;     }
;     SBAR();
.LBB0_384:
	v_mov_b64_e32 v[98:99], v[114:115]
	v_mov_b64_e32 v[100:101], v[116:117]
	v_mov_b64_e32 v[102:103], v[118:119]
	v_mov_b64_e32 v[104:105], v[120:121]
	v_mov_b64_e32 v[106:107], v[122:123]
	v_mov_b64_e32 v[108:109], v[124:125]
	v_mov_b64_e32 v[110:111], v[126:127]
	v_mov_b64_e32 v[112:113], v[128:129]
	s_branch .LBB0_385
